# group A MFMA phase at priority 3
# baseline (speedup 1.0000x reference)
; DI void diff_core(unsigned char* smem, const u16* qptr, const u16* kbase, const u16* vtbase, int vld,
;                   int ntb, int ntw, int nvalid, int ks0, const float* lut, int qpos, bool active, bool grpB,
;                   f32x16 (&O)[4], float& l_out) {
;     ...
;   auto qk = [&](int slot) {
;     if (grpB) __builtin_amdgcn_s_setprio(2); else __builtin_amdgcn_s_setprio(1);
;     const float ini = -m;
; #pragma unroll
;     for (int kb = 0; kb < 2; ++kb)
; #pragma unroll
;       for (int e = 0; e < 16; ++e) S[kb][e] = ini;
;     const LAS unsigned char* b = lds + slot * D_SLOT;
;     bf16x8 kf[4][2];
; #pragma unroll
;     ...
;   auto pv = [&](int slot) {
;     if (grpB) __builtin_amdgcn_s_setprio(2); else __builtin_amdgcn_s_setprio(1);
;     const LAS unsigned char* b = lds + slot * D_SLOT;
;     bf16x8 va[4], vb[4];
; #pragma unroll
;     for (int tt = 0; tt < 4; ++tt) va[tt] = *reinterpret_cast<const LAS bf16x8*>(b + voff[0] + tt * 32 * 128);
; #pragma unroll
;     for (int tt = 0; tt < 4; ++tt) vb[tt] = *reinterpret_cast<const LAS bf16x8*>(b + voff[1] + tt * 32 * 128);
;     {
;       const bf16x8 pf = __builtin_bit_cast(bf16x8, P[0]);
; #pragma unroll
;       for (int tt = 0; tt < 4; ++tt) O[tt] = MFMA(va[tt], pf, O[tt]);
;     }
; #pragma unroll
;     for (int tt = 0; tt < 4; ++tt) va[tt] = *reinterpret_cast<const LAS bf16x8*>(b + voff[2] + tt * 32 * 128);
;     {
;       const bf16x8 pf = __builtin_bit_cast(bf16x8, P[1]);
; #pragma unroll
;       for (int tt = 0; tt < 4; ++tt) O[tt] = MFMA(vb[tt], pf, O[tt]);
;     }
; #pragma unroll
;     for (int tt = 0; tt < 4; ++tt) vb[tt] = *reinterpret_cast<const LAS bf16x8*>(b + voff[3] + tt * 32 * 128);
;     {
;       const bf16x8 pf = __builtin_bit_cast(bf16x8, P[2]);
; #pragma unroll
;       for (int tt = 0; tt < 4; ++tt) O[tt] = MFMA(va[tt], pf, O[tt]);
;     }
;     {
;       const bf16x8 pf = __builtin_bit_cast(bf16x8, P[3]);
; #pragma unroll
;       for (int tt = 0; tt < 4; ++tt) O[tt] = MFMA(vb[tt], pf, O[tt]);
;     }
;     __builtin_amdgcn_sched_group_barrier(0x100, 8, 0);
;     __builtin_amdgcn_sched_group_barrier(0x008, 4, 0);
;     __builtin_amdgcn_sched_group_barrier(0x100, 4, 0);
;     __builtin_amdgcn_sched_group_barrier(0x008, 4, 0);
;     __builtin_amdgcn_sched_group_barrier(0x100, 4, 0);
;     __builtin_amdgcn_sched_group_barrier(0x008, 8, 0);
;     __builtin_amdgcn_s_setprio(0);
;   };
.LBB0_360:
	s_add_i32 s66, s64, 0x101
	s_cmp_gt_u32 s66, s16
	s_cbranch_scc1 .LBB0_362
	s_setprio 3
	s_and_b32 s0, s65, 0x18000
	v_add_u32_e32 v248, s0, v197
	ds_read_b128 v[64:67], v248 offset:16384
	ds_read_b128 v[68:71], v248 offset:20480
	ds_read_b128 v[72:75], v248 offset:24576
	ds_read_b128 v[76:79], v248 offset:28672
	s_add_i32 s67, s65, 0xfffe8000
	s_and_b32 s67, s67, 0x18000
	v_cvt_pk_bf16_f32 v144, v96, v97
	v_cvt_pk_bf16_f32 v145, v98, v99
	v_cvt_pk_bf16_f32 v146, v100, v101
	v_cvt_pk_bf16_f32 v147, v102, v103
	v_add_f32_e32 v250, v97, v96
	v_add_f32_e32 v250, v98, v250
	s_waitcnt lgkmcnt(4)
	v_mfma_f32_32x32x16_bf16 v[48:63], v[200:203], v[144:147], v[48:63]
	v_cvt_pk_bf16_f32 v148, v104, v105
	v_add_f32_e32 v250, v99, v250
	v_add_f32_e32 v250, v100, v250
	v_add_u32_e32 v249, s0, v198
	ds_read_b128 v[80:83], v249 offset:16384
	ds_read_b128 v[84:87], v249 offset:20480
	ds_read_b128 v[88:91], v249 offset:24576
	ds_read_b128 v[92:95], v249 offset:28672
	v_mfma_f32_32x32x16_bf16 v[32:47], v[204:207], v[144:147], v[32:47]
	v_cvt_pk_bf16_f32 v149, v106, v107
	v_add_f32_e32 v250, v101, v250
	v_add_f32_e32 v250, v102, v250
	v_mfma_f32_32x32x16_bf16 v[16:31], v[208:211], v[144:147], v[16:31]
	v_cvt_pk_bf16_f32 v150, v108, v109
	v_add_f32_e32 v250, v103, v250
	v_add_f32_e32 v250, v104, v250
	v_mfma_f32_32x32x16_bf16 v[0:15], v[212:215], v[144:147], v[0:15]
	v_cvt_pk_bf16_f32 v151, v110, v111
	v_add_f32_e32 v250, v105, v250
	v_add_f32_e32 v250, v106, v250
	v_mfma_f32_32x32x16_bf16 v[48:63], v[216:219], v[148:151], v[48:63]
	v_cvt_pk_bf16_f32 v152, v112, v113
	v_add_f32_e32 v250, v107, v250
	v_add_f32_e32 v250, v108, v250
	v_mfma_f32_32x32x16_bf16 v[32:47], v[220:223], v[148:151], v[32:47]
	v_cvt_pk_bf16_f32 v153, v114, v115
	v_add_f32_e32 v250, v109, v250
	v_add_f32_e32 v250, v110, v250
	v_mfma_f32_32x32x16_bf16 v[16:31], v[224:227], v[148:151], v[16:31]
	v_cvt_pk_bf16_f32 v154, v116, v117
	v_add_f32_e32 v250, v111, v250
	v_add_f32_e32 v250, v112, v250
	v_mfma_f32_32x32x16_bf16 v[0:15], v[228:231], v[148:151], v[0:15]
	v_cvt_pk_bf16_f32 v155, v118, v119
	v_add_f32_e32 v250, v113, v250
	v_add_f32_e32 v250, v114, v250
	v_add_u32_e32 v248, s67, v177
	ds_read_b128 v[200:203], v248
	ds_read_b128 v[204:207], v248 offset:8192
	v_add_u32_e32 v249, s67, v178
	ds_read_b128 v[208:211], v249
	ds_read_b128 v[212:215], v249 offset:8192
	s_waitcnt lgkmcnt(8)
	v_mfma_f32_32x32x16_bf16 v[48:63], v[64:67], v[152:155], v[48:63]
	v_cvt_pk_bf16_f32 v156, v120, v121
	v_add_f32_e32 v250, v115, v250
	v_add_f32_e32 v250, v116, v250
	v_mfma_f32_32x32x16_bf16 v[32:47], v[68:71], v[152:155], v[32:47]
	v_cvt_pk_bf16_f32 v157, v122, v123
	v_add_f32_e32 v250, v117, v250
	v_add_f32_e32 v250, v118, v250
	v_mfma_f32_32x32x16_bf16 v[16:31], v[72:75], v[152:155], v[16:31]
	v_cvt_pk_bf16_f32 v158, v124, v125
	v_add_f32_e32 v250, v119, v250
	v_add_f32_e32 v250, v120, v250
	v_mfma_f32_32x32x16_bf16 v[0:15], v[76:79], v[152:155], v[0:15]
	v_cvt_pk_bf16_f32 v159, v126, v127
	v_add_f32_e32 v250, v121, v250
	v_add_f32_e32 v250, v122, v250
	v_add_u32_e32 v248, s67, v179
	ds_read_b128 v[216:219], v248
	ds_read_b128 v[220:223], v248 offset:8192
	v_add_u32_e32 v249, s67, v180
	ds_read_b128 v[224:227], v249
	ds_read_b128 v[228:231], v249 offset:8192
	s_waitcnt lgkmcnt(8)
	v_mfma_f32_32x32x16_bf16 v[48:63], v[80:83], v[156:159], v[48:63]
	v_add_f32_e32 v250, v123, v250
	v_add_f32_e32 v250, v124, v250
	v_mfma_f32_32x32x16_bf16 v[32:47], v[84:87], v[156:159], v[32:47]
	v_add_f32_e32 v250, v125, v250
	v_add_f32_e32 v250, v126, v250
	v_mfma_f32_32x32x16_bf16 v[16:31], v[88:91], v[156:159], v[16:31]
	v_add_f32_e32 v250, v127, v250
	v_mfma_f32_32x32x16_bf16 v[0:15], v[92:95], v[156:159], v[0:15]
	v_add_f32_e32 v181, v181, v250
	s_setprio 0
.LBB0_362:
	s_cmp_lt_u32 s66, s16
	s_cselect_b64 s[0:1], -1, 0
	s_cmp_ge_u32 s66, s16
	s_cbranch_scc1 .LBB0_364
	s_setprio 3
	s_waitcnt lgkmcnt(0)
	v_mfma_f32_32x32x16_bf16 v[96:111], v[200:203], v[128:131], v[232:247]
	v_mfma_f32_32x32x16_bf16 v[112:127], v[204:207], v[128:131], v[232:247]
	v_mfma_f32_32x32x16_bf16 v[96:111], v[208:211], v[132:135], v[96:111]
	v_mfma_f32_32x32x16_bf16 v[112:127], v[212:215], v[132:135], v[112:127]
	v_mfma_f32_32x32x16_bf16 v[96:111], v[216:219], v[136:139], v[96:111]
	v_mfma_f32_32x32x16_bf16 v[112:127], v[220:223], v[136:139], v[112:127]
	v_mfma_f32_32x32x16_bf16 v[96:111], v[224:227], v[140:143], v[96:111]
	v_mfma_f32_32x32x16_bf16 v[112:127], v[228:231], v[140:143], v[112:127]
	s_setprio 0
